# HGRN2 mixer: exp2(b_ref) table once per chunk; St image math overlapped with the stage-1 fragment reads
# speedup vs baseline: 1.0045x; 1.0000x over previous
; template <int DK, bool IS_A, int NDV>
; __device__ __forceinline__ void mix_stream(const Params& p, LAS unsigned char* lds, int l, int rs, int T, int h, int dir, int dvh) {
;     ...
;         for (int dki = 0; dki < 2; ++dki) { f32x4 er;
;           if (IS_A) { const int dk = (tdk0 + dki) * 16 + fq * 4; const f32x4 e = *(const LAS f32x4*)(seg + dk) + *(const LAS f32x4*)(seg + DK + dk) + *(const LAS f32x4*)(seg + 2 * DK + dk) + *(const LAS f32x4*)(seg + 3 * DK + dk);
; #pragma unroll
;               for (int j = 0; j < 4; ++j) er[j] = exp2_(fmaxf(e[j], -115.f)); }
;           else { const float e = __expf(32.0f * lg); er = (f32x4){e, e, e, e}; }
; #pragma unroll
;           for (int dvi = 0; dvi < DVW; ++dvi) { const f32x4 sv = S[dki * DVW + dvi] * er; u32x2 pk; pk.x = cvt_pk_bf16(sv[0], sv[1]); pk.y = cvt_pk_bf16(sv[2], sv[3]);
;               *(LAS u32x2*)(St + ((tdv0 + dvi) * 16 + fr) * QP + ((((tdk0 + dki) * 16 + fq * 4) * 2) ^ (gx << 4))) = pk; } }
;     ...
;         { const int tt = w >> 1, ts0 = (w & 1) * 2; f32x4 pa = (f32x4){0.f, 0.f, 0.f, 0.f}, pb = pa;
;           bf16x8 gq_[KS], gk0[KS], gk1[KS];
; #pragma unroll
;           for (int ks = 0; ks < KS; ++ks) { gq_[ks] = ldfrag(Qs, QP, tt, ks, fr, fqx); gk0[ks] = ldfrag(Ks, QP, ts0, ks, fr, fqx); gk1[ks] = ldfrag(Ks, QP, ts0 + 1, ks, fr, fqx); }
;           __builtin_amdgcn_sched_barrier(0);
; #pragma unroll
;           for (int ks = 0; ks < KS; ++ks) { pa = MFMA16(gk0[ks], gq_[ks], pa); pb = MFMA16(gk1[ks], gq_[ks], pb); }
;           const int t = tt * 16 + fr, s0 = ts0 * 16 + fq * 4, s1 = s0 + 16;
;           u32x2 w0, w1;
;           w0.x = cvt_pk_bf16(t >= s0 ? pa[0] : 0.f, t >= s0 + 1 ? pa[1] : 0.f); w0.y = cvt_pk_bf16(t >= s0 + 2 ? pa[2] : 0.f, t >= s0 + 3 ? pa[3] : 0.f);
;           w1.x = cvt_pk_bf16(t >= s1 ? pb[0] : 0.f, t >= s1 + 1 ? pb[1] : 0.f); w1.y = cvt_pk_bf16(t >= s1 + 2 ? pb[2] : 0.f, t >= s1 + 3 ? pb[3] : 0.f);
;           *(LAS u32x2*)(Ps + t * TP + ((s0 * 2) ^ (gx << 4))) = w0; *(LAS u32x2*)(Ps + t * TP + ((s1 * 2) ^ (gx << 4))) = w1; }
; #pragma unroll
;         for (int ks = 0; ks < 2; ++ks) { bf16x8 ak[2], bv[DVW];
; #pragma unroll
;             for (int dki = 0; dki < 2; ++dki) ak[dki] = ldfrag(Kt, TP, tdk0 + dki, ks, fr, fqx);
; #pragma unroll
;             for (int dvi = 0; dvi < DVW; ++dvi) bv[dvi] = ldfrag(Vt, TP, tdv0 + dvi, ks, fr, fqx);
.LBB0_172:
	s_waitcnt lgkmcnt(0)
	s_barrier
	ds_read_b128 v[204:207], v130 offset:18432
	ds_read_b128 v[208:211], v130 offset:18496
	ds_read_b128 v[0:3], v137
	ds_read_b128 v[4:7], v137 offset:64
	ds_read_b128 v[90:93], v138 offset:17408
	ds_read_b128 v[94:97], v138 offset:17472
	ds_read_b128 v[98:101], v139 offset:17408
	ds_read_b128 v[102:105], v139 offset:17472
	ds_read_b128 v[166:169], v137 offset:128
	ds_read_b128 v[170:173], v137 offset:192
	ds_read_b128 v[180:183], v138 offset:17536
	ds_read_b128 v[184:187], v138 offset:17600
	ds_read_b128 v[188:191], v139 offset:17536
	ds_read_b128 v[192:195], v139 offset:17600
	s_waitcnt lgkmcnt(7)
	v_pk_mul_f32 v[214:215], v[56:57], v[204:205]
	v_pk_mul_f32 v[212:213], v[58:59], v[206:207]
	v_cvt_pk_bf16_f32 v216, v214, v215
	v_cvt_pk_bf16_f32 v217, v212, v213
	ds_write_b64 v135, v[216:217]
	v_pk_mul_f32 v[214:215], v[60:61], v[204:205]
	v_pk_mul_f32 v[212:213], v[62:63], v[206:207]
	v_cvt_pk_bf16_f32 v218, v214, v215
	v_cvt_pk_bf16_f32 v219, v212, v213
	ds_write_b64 v135, v[218:219] offset:4352
	v_pk_mul_f32 v[214:215], v[64:65], v[204:205]
	v_pk_mul_f32 v[212:213], v[66:67], v[206:207]
	v_cvt_pk_bf16_f32 v216, v214, v215
	v_cvt_pk_bf16_f32 v217, v212, v213
	ds_write_b64 v135, v[216:217] offset:8704
	v_pk_mul_f32 v[214:215], v[68:69], v[204:205]
	v_pk_mul_f32 v[212:213], v[70:71], v[206:207]
	v_cvt_pk_bf16_f32 v218, v214, v215
	v_cvt_pk_bf16_f32 v219, v212, v213
	ds_write_b64 v135, v[218:219] offset:13056
	v_pk_mul_f32 v[214:215], v[72:73], v[208:209]
	v_pk_mul_f32 v[212:213], v[74:75], v[210:211]
	v_cvt_pk_bf16_f32 v216, v214, v215
	v_cvt_pk_bf16_f32 v217, v212, v213
	ds_write_b64 v136, v[216:217]
	v_pk_mul_f32 v[214:215], v[76:77], v[208:209]
	v_pk_mul_f32 v[212:213], v[78:79], v[210:211]
	v_cvt_pk_bf16_f32 v218, v214, v215
	v_cvt_pk_bf16_f32 v219, v212, v213
	ds_write_b64 v136, v[218:219] offset:4352
	v_pk_mul_f32 v[214:215], v[80:81], v[208:209]
	v_pk_mul_f32 v[212:213], v[82:83], v[210:211]
	v_cvt_pk_bf16_f32 v216, v214, v215
	v_cvt_pk_bf16_f32 v217, v212, v213
	ds_write_b64 v136, v[216:217] offset:8704
	v_pk_mul_f32 v[214:215], v[84:85], v[208:209]
	v_pk_mul_f32 v[212:213], v[86:87], v[210:211]
	v_cvt_pk_bf16_f32 v218, v214, v215
	v_cvt_pk_bf16_f32 v219, v212, v213
	ds_write_b64 v136, v[218:219] offset:13056
	s_waitcnt lgkmcnt(15)
	v_mfma_f32_16x16x32_bf16 v[90:93], v[90:93], v[0:3], 0
	s_waitcnt lgkmcnt(15)
	v_mfma_f32_16x16x32_bf16 v[0:3], v[98:101], v[0:3], 0
	v_mfma_f32_16x16x32_bf16 v[90:93], v[94:97], v[4:7], v[90:93]
	s_waitcnt lgkmcnt(14)
	v_mfma_f32_16x16x32_bf16 v[0:3], v[102:105], v[4:7], v[0:3]
	s_waitcnt lgkmcnt(11)
	v_mfma_f32_16x16x32_bf16 v[4:7], v[180:183], v[166:169], v[90:93]
	s_waitcnt lgkmcnt(9)
	v_mfma_f32_16x16x32_bf16 v[0:3], v[188:191], v[166:169], v[0:3]
	v_mfma_f32_16x16x32_bf16 v[4:7], v[184:187], v[170:173], v[4:7]
	s_waitcnt lgkmcnt(8)
	v_mfma_f32_16x16x32_bf16 v[0:3], v[192:195], v[170:173], v[0:3]
	s_nop 5
	v_cndmask_b32_e64 v4, v4, 0, s[42:43]
	v_cndmask_b32_e64 v5, 0, v5, s[44:45]
	v_cvt_pk_bf16_f32 v4, v4, v5
	v_cndmask_b32_e64 v5, v6, 0, s[46:47]
	v_cndmask_b32_e64 v0, v0, 0, s[50:51]
	v_cndmask_b32_e64 v1, v1, 0, s[52:53]
	v_cndmask_b32_e64 v6, v7, 0, s[48:49]
	v_cvt_pk_bf16_f32 v5, v5, v6
	v_cvt_pk_bf16_f32 v0, v0, v1
	v_cndmask_b32_e64 v1, v2, 0, s[54:55]
	v_cndmask_b32_e64 v2, v3, 0, s[56:57]
	v_cvt_pk_bf16_f32 v1, v1, v2
	ds_write_b64 v140, v[4:5]
	ds_write_b64 v141, v[0:1]
	ds_read_b128 v[0:3], v142 offset:53248
	ds_read_b128 v[4:7], v143 offset:53248
	ds_read_b128 v[90:93], v144 offset:34816
	ds_read_b128 v[94:97], v144 offset:37120
	ds_read_b128 v[98:101], v144 offset:39424
	ds_read_b128 v[102:105], v144 offset:41728
	s_waitcnt lgkmcnt(3)
	v_mfma_f32_16x16x32_bf16 v[166:169], v[0:3], v[90:93], 0
	s_waitcnt lgkmcnt(2)
	v_mfma_f32_16x16x32_bf16 v[170:173], v[0:3], v[94:97], 0
	s_waitcnt lgkmcnt(1)
	v_mfma_f32_16x16x32_bf16 v[180:183], v[0:3], v[98:101], 0
	s_waitcnt lgkmcnt(0)
	v_mfma_f32_16x16x32_bf16 v[0:3], v[0:3], v[102:105], 0
	v_mfma_f32_16x16x32_bf16 v[90:93], v[4:7], v[90:93], 0
	v_mfma_f32_16x16x32_bf16 v[94:97], v[4:7], v[94:97], 0
	v_mfma_f32_16x16x32_bf16 v[98:101], v[4:7], v[98:101], 0
	v_mfma_f32_16x16x32_bf16 v[4:7], v[4:7], v[102:105], 0
	ds_read_b128 v[102:105], v142 offset:53312
	ds_read_b128 v[184:187], v143 offset:53312
	ds_read_b128 v[188:191], v144 offset:34880
	ds_read_b128 v[192:195], v144 offset:37184
	ds_read_b128 v[196:199], v144 offset:39488
	ds_read_b128 v[200:203], v144 offset:41792
	s_waitcnt lgkmcnt(3)
	v_mfma_f32_16x16x32_bf16 v[166:169], v[102:105], v[188:191], v[166:169]
	s_waitcnt lgkmcnt(2)
	v_mfma_f32_16x16x32_bf16 v[170:173], v[102:105], v[192:195], v[170:173]
	s_waitcnt lgkmcnt(1)
	v_mfma_f32_16x16x32_bf16 v[180:183], v[102:105], v[196:199], v[180:183]
	s_waitcnt lgkmcnt(0)
	v_mfma_f32_16x16x32_bf16 v[0:3], v[102:105], v[200:203], v[0:3]
	v_mfma_f32_16x16x32_bf16 v[90:93], v[184:187], v[188:191], v[90:93]
	v_mfma_f32_16x16x32_bf16 v[94:97], v[184:187], v[192:195], v[94:97]
	v_mfma_f32_16x16x32_bf16 v[98:101], v[184:187], v[196:199], v[98:101]
	v_mfma_f32_16x16x32_bf16 v[4:7], v[184:187], v[200:203], v[4:7]
	s_waitcnt lgkmcnt(0)
	s_barrier
; #define LAS __attribute__((address_space(3)))
; template <int DK, bool IS_A, int NDV>
; __device__ __forceinline__ void mix_stream(const Params& p, LAS unsigned char* lds, int l, int rs, int T, int h, int dir, int dvh) {
;     ...
;         { const int tp = w >> 2, dp = w & 3; f32x4 o[4];
; #pragma unroll
;           for (int q = 0; q < 4; ++q) o[q] = (f32x4){0.f, 0.f, 0.f, 0.f};
; #pragma unroll
;           for (int kb = 0; kb < KS; kb += 2) { bf16x8 b[2][2], a[2][2];
; #pragma unroll
;               for (int k2 = 0; k2 < 2; ++k2)
; #pragma unroll
;                   for (int i2 = 0; i2 < 2; ++i2) { b[k2][i2] = ldfrag(Qs, QP, 2 * tp + i2, kb + k2, fr, fqx); a[k2][i2] = ldfrag(St, QP, 2 * dp + i2, kb + k2, fr, fqx); }
;               __builtin_amdgcn_sched_barrier(0);
; #pragma unroll
;               for (int k2 = 0; k2 < 2; ++k2)
; #pragma unroll
;                   for (int ti = 0; ti < 2; ++ti)
; #pragma unroll
;                       for (int di = 0; di < 2; ++di) o[ti * 2 + di] = MFMA16(a[k2][di], b[k2][ti], o[ti * 2 + di]);
;               __builtin_amdgcn_sched_barrier(0); }
;           { bf16x8 b[2][2], a[2][2];
; #pragma unroll
;               for (int k2 = 0; k2 < 2; ++k2)
; #pragma unroll
;                   for (int i2 = 0; i2 < 2; ++i2) { b[k2][i2] = ldfrag(Ps, TP, 2 * tp + i2, k2, fr, fqx); a[k2][i2] = ldfrag(Vt, TP, 2 * dp + i2, k2, fr, fqx); }
;               __builtin_amdgcn_sched_barrier(0);
; #pragma unroll
;               for (int k2 = 0; k2 < 2; ++k2)
; #pragma unroll
;                   for (int ti = 0; ti < 2; ++ti)
; #pragma unroll
;                       for (int di = 0; di < 2; ++di) o[ti * 2 + di] = MFMA16(a[k2][di], b[k2][ti], o[ti * 2 + di]);
;               __builtin_amdgcn_sched_barrier(0); }
; #pragma unroll
;           for (int ti = 0; ti < 2; ++ti)
; #pragma unroll
;               for (int di = 0; di < 2; ++di) { const f32x4 ov = o[ti * 2 + di]; u32x2 pk; pk.x = cvt_pk_bf16(ov[0], ov[1]); pk.y = cvt_pk_bf16(ov[2], ov[3]);
;                   *(LAS u32x2*)(Os + ((2 * tp + ti) * 16 + fr) * OP + ((2 * dp + di) * 16 + fq * 4) * 2) = pk; } }
; #pragma unroll
;         for (int dki = 0; dki < 2; ++dki) { f32x4 cd, cs;
;           if (IS_A) { cd = *(const LAS f32x4*)(cdec + (tdk0 + dki) * 16 + fq * 4); cs = *(const LAS f32x4*)(csc + (tdk0 + dki) * 16 + fq * 4); }
	v_add_u32_e32 v174, v111, v126
	ds_read_b128 v[102:105], v174
	ds_read_b128 v[184:187], v174 offset:64
	ds_read_b128 v[188:191], v145
	ds_read_b128 v[192:195], v145 offset:64
	ds_read_b128 v[196:199], v174 offset:4352
	ds_read_b128 v[200:203], v174 offset:4416
	ds_read_b128 v[204:207], v146
	ds_read_b128 v[208:211], v146 offset:64
	s_waitcnt lgkmcnt(5)
	v_mfma_f32_16x16x32_bf16 v[212:215], v[188:191], v[102:105], 0
	s_waitcnt lgkmcnt(1)
	v_mfma_f32_16x16x32_bf16 v[102:105], v[204:207], v[102:105], 0
	v_mfma_f32_16x16x32_bf16 v[188:191], v[188:191], v[196:199], 0
	v_mfma_f32_16x16x32_bf16 v[196:199], v[204:207], v[196:199], 0
	v_mfma_f32_16x16x32_bf16 v[204:207], v[192:195], v[184:187], v[212:215]
	s_waitcnt lgkmcnt(0)
	v_mfma_f32_16x16x32_bf16 v[102:105], v[208:211], v[184:187], v[102:105]
	v_mfma_f32_16x16x32_bf16 v[184:187], v[192:195], v[200:203], v[188:191]
	v_mfma_f32_16x16x32_bf16 v[188:191], v[208:211], v[200:203], v[196:199]
	ds_read_b128 v[192:195], v174 offset:128
	s_nop 1
	ds_read_b128 v[196:199], v174 offset:192
	ds_read_b128 v[200:203], v145 offset:128
	ds_read_b128 v[208:211], v145 offset:192
	ds_read_b128 v[212:215], v174 offset:4480
	ds_read_b128 v[216:219], v174 offset:4544
	ds_read_b128 v[220:223], v146 offset:128
	ds_read_b128 v[224:227], v146 offset:192
	s_waitcnt lgkmcnt(5)
	v_mfma_f32_16x16x32_bf16 v[204:207], v[200:203], v[192:195], v[204:207]
	s_waitcnt lgkmcnt(1)
	v_mfma_f32_16x16x32_bf16 v[102:105], v[220:223], v[192:195], v[102:105]
	v_mfma_f32_16x16x32_bf16 v[184:187], v[200:203], v[212:215], v[184:187]
	v_mfma_f32_16x16x32_bf16 v[188:191], v[220:223], v[212:215], v[188:191]
	v_mfma_f32_16x16x32_bf16 v[192:195], v[208:211], v[196:199], v[204:207]
	s_waitcnt lgkmcnt(0)
	v_mfma_f32_16x16x32_bf16 v[102:105], v[224:227], v[196:199], v[102:105]
	v_mfma_f32_16x16x32_bf16 v[184:187], v[208:211], v[216:219], v[184:187]
	v_mfma_f32_16x16x32_bf16 v[188:191], v[224:227], v[216:219], v[188:191]
	ds_read_b128 v[196:199], v148
	ds_read_b128 v[200:203], v148 offset:64
	ds_read_b128 v[204:207], v142 offset:34816
	ds_read_b128 v[208:211], v142 offset:34880
	ds_read_b128 v[212:215], v148 offset:2304
	ds_read_b128 v[216:219], v148 offset:2368
	ds_read_b128 v[220:223], v143 offset:34816
	ds_read_b128 v[224:227], v143 offset:34880
	s_waitcnt lgkmcnt(5)
	v_mfma_f32_16x16x32_bf16 v[192:195], v[204:207], v[196:199], v[192:195]
	s_waitcnt lgkmcnt(1)
	v_mfma_f32_16x16x32_bf16 v[102:105], v[220:223], v[196:199], v[102:105]
	v_mfma_f32_16x16x32_bf16 v[184:187], v[204:207], v[212:215], v[184:187]
	v_mfma_f32_16x16x32_bf16 v[188:191], v[220:223], v[212:215], v[188:191]
	v_mfma_f32_16x16x32_bf16 v[192:195], v[208:211], v[200:203], v[192:195]
	s_waitcnt lgkmcnt(0)
	v_mfma_f32_16x16x32_bf16 v[102:105], v[224:227], v[200:203], v[102:105]
	v_mfma_f32_16x16x32_bf16 v[184:187], v[208:211], v[216:219], v[184:187]
	v_mfma_f32_16x16x32_bf16 v[188:191], v[224:227], v[216:219], v[188:191]
	v_cvt_pk_bf16_f32 v102, v102, v103
	v_cvt_pk_bf16_f32 v103, v104, v105
	s_nop 5
	v_add_u32_e32 v104, s10, v128
	ds_write_b64 v104, v[102:103]
	v_add_u32_e32 v104, s14, v156
	v_add_u32_e32 v179, s14, v128
	v_cvt_pk_bf16_f32 v102, v184, v185
	v_cvt_pk_bf16_f32 v103, v186, v187
	ds_write_b64 v104, v[102:103]
	v_add_u32_e32 v104, s10, v156
	v_cvt_pk_bf16_f32 v174, v192, v193
	v_cvt_pk_bf16_f32 v175, v194, v195
	ds_write_b64 v179, v[174:175]
	v_cvt_pk_bf16_f32 v102, v188, v189
	v_cvt_pk_bf16_f32 v103, v190, v191
	ds_write_b64 v104, v[102:103]
	ds_read_b128 v[102:105], v131
	ds_read_b128 v[184:187], v130
	ds_read_b128 v[188:191], v131 offset:64
	s_add_i32 s11, s11, 64
	s_sub_i32 s19, s19, 64
	s_waitcnt lgkmcnt(2)
	v_pk_mul_f32 v[174:175], v[168:169], v[104:105]
	v_pk_mul_f32 v[192:193], v[166:167], v[102:103]
	ds_read_b128 v[166:169], v130 offset:64
	v_pk_mul_f32 v[2:3], v[2:3], v[104:105]
	v_pk_mul_f32 v[0:1], v[0:1], v[102:103]
	s_waitcnt lgkmcnt(2)
	v_pk_fma_f32 v[70:71], v[70:71], v[186:187], v[2:3]
	v_pk_fma_f32 v[68:69], v[68:69], v[184:185], v[0:1]
	s_waitcnt lgkmcnt(1)
	v_pk_mul_f32 v[0:1], v[92:93], v[190:191]
	v_pk_mul_f32 v[2:3], v[90:91], v[188:189]
	s_waitcnt lgkmcnt(0)
	v_pk_fma_f32 v[74:75], v[74:75], v[168:169], v[0:1]
	v_pk_fma_f32 v[72:73], v[72:73], v[166:167], v[2:3]
	v_pk_mul_f32 v[0:1], v[96:97], v[190:191]
	v_pk_mul_f32 v[2:3], v[94:95], v[188:189]
	v_pk_mul_f32 v[172:173], v[172:173], v[104:105]
	v_pk_mul_f32 v[170:171], v[170:171], v[102:103]
	v_pk_fma_f32 v[78:79], v[78:79], v[168:169], v[0:1]
	v_pk_fma_f32 v[76:77], v[76:77], v[166:167], v[2:3]
	v_pk_mul_f32 v[0:1], v[100:101], v[190:191]
	v_pk_mul_f32 v[2:3], v[98:99], v[188:189]
	v_pk_fma_f32 v[62:63], v[62:63], v[186:187], v[172:173]
	v_pk_fma_f32 v[60:61], v[60:61], v[184:185], v[170:171]
	v_pk_mul_f32 v[170:171], v[182:183], v[104:105]
	v_pk_mul_f32 v[172:173], v[180:181], v[102:103]
	v_pk_fma_f32 v[82:83], v[82:83], v[168:169], v[0:1]
	v_pk_fma_f32 v[80:81], v[80:81], v[166:167], v[2:3]
	v_pk_mul_f32 v[0:1], v[6:7], v[190:191]
	v_pk_mul_f32 v[2:3], v[4:5], v[188:189]
	v_pk_fma_f32 v[58:59], v[58:59], v[186:187], v[174:175]
	v_pk_fma_f32 v[56:57], v[56:57], v[184:185], v[192:193]
	v_pk_fma_f32 v[66:67], v[66:67], v[186:187], v[170:171]
	v_pk_fma_f32 v[64:65], v[64:65], v[184:185], v[172:173]
	v_pk_fma_f32 v[86:87], v[86:87], v[168:169], v[0:1]
	s_cmp_lg_u32 s78, s17
	v_pk_fma_f32 v[84:85], v[84:85], v[166:167], v[2:3]
	s_cbranch_scc0 .LBB0_149

; #define LAS __attribute__((address_space(3)))
; __device__ __forceinline__ unsigned cvt_pk_bf16(float lo, float hi) { unsigned r; asm("v_cvt_pk_bf16_f32 %0, %1, %2" : "=v"(r) : "v"(lo), "v"(hi)); return r; }
; __device__ __forceinline__ float bf_lo(unsigned u) { return __uint_as_float(u << 16); }
; __device__ __forceinline__ float bf_hi(unsigned u) { return __uint_as_float(u & 0xffff0000u); }
; template <int DK, bool IS_A, int NDV>
; __device__ __forceinline__ void mix_stream(const Params& p, LAS unsigned char* lds, int l, int rs, int T, int h, int dir, int dvh) {
;     ...
;                 float pre0 = 0.f, pre1 = 0.f, ref0 = 0.f, ref1 = 0.f, tot0 = 0.f, tot1 = 0.f;
; #pragma unroll
;                 for (int s8 = 0; s8 < 8; ++s8) { const f32x2 v = *(const LAS f32x2*)(seg + s8 * DK + 2 * cp);
;                     if (s8 < sg) { pre0 += v.x; pre1 += v.y; } if (s8 < 4) { ref0 += v.x; ref1 += v.y; } tot0 += v.x; tot1 += v.y; }
;                 f32x2 E = (f32x2){exp2_(fminf(fmaxf(pre0 - ref0, -115.f), 115.f)), exp2_(fminf(fmaxf(pre1 - ref1, -115.f), 115.f))};
; #pragma unroll
;                 for (int ip = 0; ip < 4; ++ip) { unsigned kp[2];
; #pragma unroll
;                     for (int e = 0; e < 2; ++e) { const int i = 2 * ip + e;
;                         const f32x2 f = (f32x2){exp2_(bf_lo(rf[par][i])), exp2_(bf_hi(rf[par][i]))};
;                         E = __builtin_elementwise_max(E * f, (f32x2){1e-35f, 1e-35f});
;                         const f32x2 r = (f32x2){rcp_(E.x), rcp_(E.y)};
;                         const f32x2 k = r - f * r;
;                         const f32x2 qv = (f32x2){bf_lo(rq[par][i]), bf_hi(rq[par][i])} * E;
;                         const int t = sg * 8 + i;
;                         const int cb4 = (4 * cp) ^ ((i >= 4 ? 16 : 0) ^ sgx);
;                         *(LAS unsigned*)(Qs + t * QP + cb4) = cvt_pk_bf16(qv.x, qv.y);
;                         kp[e] = cvt_pk_bf16(k.x, k.y);
;                         *(LAS unsigned*)(Ks + t * QP + cb4) = kp[e]; }
;                     kt0[ip] = __builtin_amdgcn_perm(kp[1], kp[0], 0x05040100u); kt1[ip] = __builtin_amdgcn_perm(kp[1], kp[0], 0x07060302u);
;                     vt0[ip] = __builtin_amdgcn_perm(rv[par][2 * ip + 1], rv[par][2 * ip], 0x05040100u); vt1[ip] = __builtin_amdgcn_perm(rv[par][2 * ip + 1], rv[par][2 * ip], 0x07060302u);
;                 }
.LBB0_175:
	ds_read2st64_b64 v[0:3], v108 offset1:1
	v_exp_f32_e32 v104, v104
	v_exp_f32_e32 v105, v105
	v_exp_f32_e32 v102, v102
	v_exp_f32_e32 v103, v103
	s_waitcnt lgkmcnt(0)
	v_add_f32_e32 v0, 0, v0
	v_add_f32_e32 v1, 0, v1
	v_cndmask_b32_e64 v4, 0, v1, s[58:59]
	v_cndmask_b32_e64 v5, 0, v0, s[58:59]
	v_add_f32_e32 v6, v2, v5
	v_add_f32_e32 v7, v3, v4
	v_cndmask_b32_e64 v4, v4, v7, s[60:61]
	v_cndmask_b32_e64 v5, v5, v6, s[60:61]
	v_add_f32_e32 v6, v0, v2
	v_add_f32_e32 v7, v1, v3
	ds_read2st64_b64 v[0:3], v108 offset0:2 offset1:3
	v_exp_f32_e32 v100, v100
	v_exp_f32_e32 v101, v101
	v_exp_f32_e32 v98, v98
	v_exp_f32_e32 v99, v99
	s_waitcnt lgkmcnt(0)
	v_add_f32_e32 v166, v0, v5
	v_add_f32_e32 v167, v1, v4
	v_cndmask_b32_e64 v4, v4, v167, s[62:63]
	v_cndmask_b32_e64 v5, v5, v166, s[62:63]
	v_add_f32_e32 v0, v6, v0
	v_add_f32_e32 v1, v7, v1
	v_add_f32_e32 v6, v2, v5
	v_add_f32_e32 v7, v3, v4
	v_add_f32_e32 v167, v0, v2
	v_add_f32_e32 v166, v1, v3
	ds_read2st64_b64 v[0:3], v108 offset0:4 offset1:5
	v_cndmask_b32_e64 v4, v4, v7, s[64:65]
	v_cndmask_b32_e64 v5, v5, v6, s[64:65]
	v_exp_f32_e32 v96, v96
	v_exp_f32_e32 v97, v97
	s_waitcnt lgkmcnt(0)
	v_add_f32_e32 v6, v0, v5
	v_add_f32_e32 v7, v1, v4
	v_cndmask_b32_e64 v4, v4, v7, s[66:67]
	v_cndmask_b32_e64 v5, v5, v6, s[66:67]
	v_add_f32_e32 v6, v2, v5
	v_add_f32_e32 v7, v3, v4
	v_cndmask_b32_e64 v168, v4, v7, s[68:69]
	v_cndmask_b32_e64 v169, v5, v6, s[68:69]
	ds_read2st64_b64 v[4:7], v108 offset0:6 offset1:7
	v_add_u32_e32 v172, s9, v112
	v_exp_f32_e32 v94, v94
	v_exp_f32_e32 v95, v95
	v_exp_f32_e32 v92, v92
	s_waitcnt lgkmcnt(0)
	v_add_f32_e32 v170, v4, v169
	v_add_f32_e32 v171, v5, v168
	v_cndmask_b32_e64 v168, v168, v171, s[70:71]
	v_cndmask_b32_e64 v169, v169, v170, s[70:71]
	v_add_f32_e32 v170, v6, v169
	v_add_f32_e32 v171, v7, v168
	v_cndmask_b32_e64 v171, v168, v171, s[72:73]
	v_cndmask_b32_e64 v168, v169, v170, s[72:73]
	v_sub_f32_e32 v168, v168, v167
	v_sub_f32_e32 v169, v171, v166
	v_med3_f32 v168, v168, s2, v240
	v_med3_f32 v169, v169, s2, v240
	v_exp_f32_e32 v168, v168
	v_exp_f32_e32 v169, v169
	v_exp_f32_e32 v93, v93
	v_exp_f32_e32 v90, v90
	v_exp_f32_e32 v91, v91
	v_pk_mul_f32 v[168:169], v[104:105], v[168:169]
	s_andn2_b64 vcc, exec, s[0:1]
	v_max_f32_e32 v169, 0x554ad2e, v169
	v_max_f32_e32 v168, 0x554ad2e, v168
	v_rcp_f32_e32 v170, v168
	v_rcp_f32_e32 v171, v169
	s_nop 0
	v_pk_fma_f32 v[104:105], v[104:105], v[170:171], v[170:171] neg_lo:[1,0,0] neg_hi:[1,0,0]
	v_lshlrev_b32_e32 v170, 16, v122
	v_and_b32_e32 v171, 0xffff0000, v122
	v_pk_mul_f32 v[170:171], v[168:169], v[170:171]
	v_pk_mul_f32 v[168:169], v[102:103], v[168:169]
	v_cvt_pk_bf16_f32 v170, v170, v171
	v_add_u32_e32 v171, s8, v112
	v_max_f32_e32 v169, 0x554ad2e, v169
	v_max_f32_e32 v168, 0x554ad2e, v168
	v_cvt_pk_bf16_f32 v104, v104, v105
	ds_write2st64_b32 v171, v170, v104 offset1:68
	v_rcp_f32_e32 v170, v168
	v_rcp_f32_e32 v171, v169
	s_nop 0
	v_pk_fma_f32 v[102:103], v[102:103], v[170:171], v[170:171] neg_lo:[1,0,0] neg_hi:[1,0,0]
	v_lshlrev_b32_e32 v170, 16, v124
	v_and_b32_e32 v171, 0xffff0000, v124
	v_pk_mul_f32 v[170:171], v[168:169], v[170:171]
	v_pk_mul_f32 v[168:169], v[100:101], v[168:169]
	v_cvt_pk_bf16_f32 v105, v170, v171
	v_cvt_pk_bf16_f32 v102, v102, v103
	s_nop 0
	v_max_f32_e32 v169, 0x554ad2e, v169
	v_max_f32_e32 v168, 0x554ad2e, v168
	v_rcp_f32_e32 v170, v168
	v_rcp_f32_e32 v171, v169
	s_nop 0
	v_pk_fma_f32 v[100:101], v[100:101], v[170:171], v[170:171] neg_lo:[1,0,0] neg_hi:[1,0,0]
	v_lshlrev_b32_e32 v170, 16, v129
	v_and_b32_e32 v171, 0xffff0000, v129
	v_pk_mul_f32 v[170:171], v[168:169], v[170:171]
	v_pk_mul_f32 v[168:169], v[98:99], v[168:169]
	v_cvt_pk_bf16_f32 v103, v170, v171
	v_cvt_pk_bf16_f32 v100, v100, v101
	v_add_u32_e32 v101, 0x4400, v172
	v_max_f32_e32 v169, 0x554ad2e, v169
	v_max_f32_e32 v168, 0x554ad2e, v168
	v_rcp_f32_e32 v170, v168
	v_rcp_f32_e32 v171, v169
	ds_write2_b32 v101, v102, v100 offset1:68
	ds_write2_b32 v172, v105, v103 offset1:68
	v_pk_fma_f32 v[98:99], v[98:99], v[170:171], v[170:171] neg_lo:[1,0,0] neg_hi:[1,0,0]
	v_lshlrev_b32_e32 v170, 16, v150
	v_and_b32_e32 v171, 0xffff0000, v150
	v_pk_mul_f32 v[170:171], v[168:169], v[170:171]
	v_pk_mul_f32 v[168:169], v[96:97], v[168:169]
	v_cvt_pk_bf16_f32 v101, v170, v171
	v_cvt_pk_bf16_f32 v98, v98, v99
	ds_write_b32 v172, v101 offset:544
	v_max_f32_e32 v169, 0x554ad2e, v169
	v_max_f32_e32 v168, 0x554ad2e, v168
	v_rcp_f32_e32 v170, v168
	v_rcp_f32_e32 v171, v169
	v_add_u32_e32 v101, 0x200, v133
	ds_write_b32 v172, v98 offset:17952
	v_pk_fma_f32 v[96:97], v[96:97], v[170:171], v[170:171] neg_lo:[1,0,0] neg_hi:[1,0,0]
	v_lshlrev_b32_e32 v170, 16, v153
	v_and_b32_e32 v171, 0xffff0000, v153
	v_pk_mul_f32 v[170:171], v[168:169], v[170:171]
	v_pk_mul_f32 v[168:169], v[94:95], v[168:169]
	v_cvt_pk_bf16_f32 v99, v170, v171
	v_cvt_pk_bf16_f32 v96, v96, v97
	s_nop 0
	v_max_f32_e32 v169, 0x554ad2e, v169
	v_max_f32_e32 v168, 0x554ad2e, v168
	v_rcp_f32_e32 v170, v168
	v_rcp_f32_e32 v171, v169
	s_nop 0
	v_pk_fma_f32 v[94:95], v[94:95], v[170:171], v[170:171] neg_lo:[1,0,0] neg_hi:[1,0,0]
	v_lshlrev_b32_e32 v170, 16, v157
	v_and_b32_e32 v171, 0xffff0000, v157
	v_pk_mul_f32 v[170:171], v[168:169], v[170:171]
	v_pk_mul_f32 v[168:169], v[92:93], v[168:169]
	v_cvt_pk_bf16_f32 v97, v170, v171
	v_cvt_pk_bf16_f32 v94, v94, v95
	v_add_u32_e32 v95, 0x4600, v133
	v_max_f32_e32 v169, 0x554ad2e, v169
	v_max_f32_e32 v168, 0x554ad2e, v168
	v_rcp_f32_e32 v170, v168
	v_rcp_f32_e32 v171, v169
	ds_write2_b32 v95, v96, v94 offset0:76 offset1:144
	ds_write2_b32 v101, v99, v97 offset0:76 offset1:144
	v_add_u32_e32 v97, 0x400, v133
	v_pk_fma_f32 v[92:93], v[92:93], v[170:171], v[170:171] neg_lo:[1,0,0] neg_hi:[1,0,0]
	v_lshlrev_b32_e32 v170, 16, v160
	v_and_b32_e32 v171, 0xffff0000, v160
	v_pk_mul_f32 v[170:171], v[168:169], v[170:171]
	v_pk_mul_f32 v[168:169], v[90:91], v[168:169]
	v_cvt_pk_bf16_f32 v95, v170, v171
	v_cvt_pk_bf16_f32 v92, v92, v93
	s_nop 0
	v_max_f32_e32 v169, 0x554ad2e, v169
	v_max_f32_e32 v168, 0x554ad2e, v168
	v_rcp_f32_e32 v170, v168
	v_rcp_f32_e32 v171, v169
	s_nop 0
	v_pk_fma_f32 v[90:91], v[90:91], v[170:171], v[170:171] neg_lo:[1,0,0] neg_hi:[1,0,0]
	v_lshlrev_b32_e32 v170, 16, v163
	v_and_b32_e32 v171, 0xffff0000, v163
	v_cvt_pk_bf16_f32 v90, v90, v91
	v_add_u32_e32 v91, 0x4800, v133
	v_pk_mul_f32 v[168:169], v[168:169], v[170:171]
	ds_write2_b32 v91, v92, v90 offset0:84 offset1:152
	v_cvt_pk_bf16_f32 v93, v168, v169
	ds_write2_b32 v97, v95, v93 offset0:84 offset1:152
	s_cbranch_vccnz .LBB0_177
; #define LAS __attribute__((address_space(3)))
; __device__ __forceinline__ float exp2_(float x) { return __builtin_amdgcn_exp2f(x); }
; template <int DK, bool IS_A, int NDV>
; __device__ __forceinline__ void mix_stream(const Params& p, LAS unsigned char* lds, int l, int rs, int T, int h, int dir, int dvh) {
;     ...
;                 if (sg == 0) { *(LAS f32x2*)(cdec + 2 * cp) = (f32x2){exp2_(fmaxf(tot0, -115.f)), exp2_(fmaxf(tot1, -115.f))};
;                                *(LAS f32x2*)(csc + 2 * cp) = (f32x2){exp2_(fmaxf(tot0 - ref0, -115.f)), exp2_(fmaxf(tot1 - ref1, -115.f))}; }
;     ...
;           if (IS_A) { const int dk = (tdk0 + dki) * 16 + fq * 4; const f32x4 e = *(const LAS f32x4*)(seg + dk) + *(const LAS f32x4*)(seg + DK + dk) + *(const LAS f32x4*)(seg + 2 * DK + dk) + *(const LAS f32x4*)(seg + 3 * DK + dk);
; #pragma unroll
;               for (int j = 0; j < 4; ++j) er[j] = exp2_(fmaxf(e[j], -115.f)); }
	v_add_f32_e32 v1, v166, v1
	v_add_f32_e32 v0, v167, v0
	v_add_f32_e32 v1, v1, v3
	v_add_f32_e32 v0, v0, v2
	v_add_f32_e32 v1, v1, v5
	v_add_f32_e32 v0, v0, v4
	v_add_f32_e32 v3, v1, v7
	v_add_f32_e32 v2, v0, v6
	v_max_f32_e32 v0, 0xc2e60000, v2
	v_max_f32_e32 v1, 0xc2e60000, v3
	v_sub_f32_e32 v2, v2, v167
	v_sub_f32_e32 v3, v3, v166
	v_exp_f32_e32 v0, v0
	v_exp_f32_e32 v1, v1
	v_max_f32_e32 v2, 0xc2e60000, v2
	v_max_f32_e32 v3, 0xc2e60000, v3
	v_exp_f32_e32 v2, v2
	v_exp_f32_e32 v3, v3
	ds_write_b64 v109, v[0:1]
	ds_write_b64 v110, v[2:3]
	v_max_f32_e32 v4, 0xc2e60000, v167
	v_max_f32_e32 v5, 0xc2e60000, v166
	v_exp_f32_e32 v4, v4
	v_exp_f32_e32 v5, v5
	s_nop 0
	ds_write_b64 v109, v[4:5] offset:18432
